# attention: per-tile VALU test 'running max == 0 in all lanes' replaced by a sticky SGPR flag set in the rescale block (7.12-style shortening of the wave-uniform branch test)
# baseline (speedup 1.0000x reference)
.LBB0_952:
	s_waitcnt vmcnt(4)
	ds_write_b128 v207, v[112:115]
	s_waitcnt vmcnt(3)
	ds_write_b128 v207, v[116:119] offset:128
	s_waitcnt vmcnt(2)
	ds_write_b128 v207, v[120:123] offset:256
	s_waitcnt vmcnt(1)
	ds_write_b128 v208, v[124:127] offset:25600
	s_waitcnt vmcnt(0)
	ds_write_b128 v208, v[128:131] offset:25664
	s_waitcnt lgkmcnt(0)
	s_cmp_lt_i32 s2, 1
	s_waitcnt lgkmcnt(0)
	s_barrier
	s_cbranch_scc1 .LBB0_964
	v_mov_b32_e32 v14, v0
	v_mov_b32_e32 v15, v0
	v_lshl_add_u64 v[196:197], v[2:3], 0, s[6:7]
	v_mov_b32_e32 v1, v0
	v_mov_b32_e32 v2, v0
	v_mov_b32_e32 v3, v0
	v_mov_b32_e32 v4, v0
	v_mov_b32_e32 v5, v0
	v_mov_b32_e32 v6, v0
	v_mov_b32_e32 v7, v0
	v_mov_b32_e32 v8, v0
	v_mov_b32_e32 v9, v0
	v_mov_b32_e32 v10, v0
	v_mov_b32_e32 v11, v0
	v_mov_b32_e32 v12, v0
	v_mov_b32_e32 v13, v0
	v_mov_b64_e32 v[30:31], v[14:15]
	v_mov_b64_e32 v[46:47], v[14:15]
	v_mov_b64_e32 v[62:63], v[14:15]
	v_mov_b64_e32 v[78:79], v[14:15]
	v_lshl_add_u64 v[198:199], s[30:31], 0, v[194:195]
	s_mov_b32 s35, 0
	v_mov_b32_e32 v214, 0
	s_mov_b32 s100, 0
	v_mov_b32_e32 v213, 0
	v_mov_b64_e32 v[28:29], v[12:13]
	v_mov_b64_e32 v[26:27], v[10:11]
	v_mov_b64_e32 v[24:25], v[8:9]
	v_mov_b64_e32 v[22:23], v[6:7]
	v_mov_b64_e32 v[20:21], v[4:5]
	v_mov_b64_e32 v[18:19], v[2:3]
	v_mov_b64_e32 v[16:17], v[0:1]
	v_mov_b64_e32 v[44:45], v[12:13]
	v_mov_b64_e32 v[42:43], v[10:11]
	v_mov_b64_e32 v[40:41], v[8:9]
	v_mov_b64_e32 v[38:39], v[6:7]
	v_mov_b64_e32 v[36:37], v[4:5]
	v_mov_b64_e32 v[34:35], v[2:3]
	v_mov_b64_e32 v[32:33], v[0:1]
	v_mov_b64_e32 v[60:61], v[12:13]
	v_mov_b64_e32 v[58:59], v[10:11]
	v_mov_b64_e32 v[56:57], v[8:9]
	v_mov_b64_e32 v[54:55], v[6:7]
	v_mov_b64_e32 v[52:53], v[4:5]
	v_mov_b64_e32 v[50:51], v[2:3]
	v_mov_b64_e32 v[48:49], v[0:1]
	v_mov_b64_e32 v[76:77], v[12:13]
	v_mov_b64_e32 v[74:75], v[10:11]
	v_mov_b64_e32 v[72:73], v[8:9]
	v_mov_b64_e32 v[70:71], v[6:7]
	v_mov_b64_e32 v[68:69], v[4:5]
	v_mov_b64_e32 v[66:67], v[2:3]
	v_mov_b64_e32 v[64:65], v[0:1]

.LBB0_961:
	s_bitcmp1_b32 s35, 0
	s_cselect_b32 s35, 0xac00, 0
	s_add_i32 s35, s35, 0
	v_add3_u32 v1, s35, v209, v204
	ds_read_b128 v[2:5], v1
	ds_read_b128 v[6:9], v1 offset:32
	ds_read_b128 v[10:13], v1 offset:12800
	ds_read_b128 v[96:99], v1 offset:12832
	v_add_u32_e32 v14, s35, v210
	ds_read_b128 v[180:183], v1 offset:64
	ds_read_b128 v[216:219], v1 offset:96
	ds_read_b128 v[220:223], v1 offset:12864
	ds_read_b128 v[224:227], v1 offset:12896
	s_waitcnt lgkmcnt(5)
	v_mfma_f32_32x32x16_bf16 v[80:95], v[10:13], v[132:135], 0
	s_waitcnt lgkmcnt(4)
	v_mfma_f32_32x32x16_bf16 v[80:95], v[96:99], v[136:139], v[80:95]
	v_mfma_f32_32x32x16_bf16 v[96:111], v[2:5], v[132:135], 0
	ds_read_b128 v[2:5], v1 offset:128
	ds_read_b128 v[10:13], v1 offset:160
	ds_read_b128 v[228:231], v1 offset:12928
	ds_read_b128 v[232:235], v1 offset:12960
	v_mfma_f32_32x32x16_bf16 v[96:111], v[6:9], v[136:139], v[96:111]
	s_waitcnt lgkmcnt(7)
	v_mfma_f32_32x32x16_bf16 v[96:111], v[180:183], v[140:143], v[96:111]
	s_waitcnt lgkmcnt(5)
	v_mfma_f32_32x32x16_bf16 v[80:95], v[220:223], v[140:143], v[80:95]
	v_mfma_f32_32x32x16_bf16 v[96:111], v[216:219], v[144:147], v[96:111]
	ds_read_b128 v[6:9], v1 offset:192
	ds_read_b128 v[180:183], v1 offset:224
	ds_read_b128 v[216:219], v1 offset:12992
	ds_read_b128 v[220:223], v1 offset:13024
	s_waitcnt lgkmcnt(8)
	v_mfma_f32_32x32x16_bf16 v[80:95], v[224:227], v[144:147], v[80:95]
	s_waitcnt lgkmcnt(7)
	v_mfma_f32_32x32x16_bf16 v[96:111], v[2:5], v[148:151], v[96:111]
	s_waitcnt lgkmcnt(5)
	v_mfma_f32_32x32x16_bf16 v[80:95], v[228:231], v[148:151], v[80:95]
	v_mfma_f32_32x32x16_bf16 v[96:111], v[10:13], v[152:155], v[96:111]
	ds_read_b128 v[2:5], v1 offset:256
	ds_read_b128 v[10:13], v1 offset:288
	ds_read_b128 v[224:227], v1 offset:13056
	ds_read_b128 v[228:231], v1 offset:13088
	s_waitcnt lgkmcnt(8)
	v_mfma_f32_32x32x16_bf16 v[80:95], v[232:235], v[152:155], v[80:95]
	s_waitcnt lgkmcnt(7)
	v_mfma_f32_32x32x16_bf16 v[96:111], v[6:9], v[156:159], v[96:111]
	s_waitcnt lgkmcnt(5)
	v_mfma_f32_32x32x16_bf16 v[80:95], v[216:219], v[156:159], v[80:95]
	ds_read_b128 v[216:219], v1 offset:320
	ds_read_b128 v[232:235], v1 offset:352
	ds_read_b128 v[236:239], v1 offset:13120
	ds_read_b128 v[240:243], v1 offset:13152
	v_mfma_f32_32x32x16_bf16 v[96:111], v[180:183], v[160:163], v[96:111]
	s_waitcnt lgkmcnt(8)
	v_mfma_f32_32x32x16_bf16 v[80:95], v[220:223], v[160:163], v[80:95]
	v_add_u32_e32 v1, v14, v204
	s_waitcnt lgkmcnt(7)
	v_mfma_f32_32x32x16_bf16 v[96:111], v[2:5], v[164:167], v[96:111]
	s_waitcnt lgkmcnt(5)
	v_mfma_f32_32x32x16_bf16 v[80:95], v[224:227], v[164:167], v[80:95]
	v_mfma_f32_32x32x16_bf16 v[96:111], v[10:13], v[168:171], v[96:111]
	ds_read_b128 v[180:183], v1 offset:25600
	ds_read_b128 v[10:13], v1 offset:25632
	ds_read_b128 v[6:9], v1 offset:25664
	ds_read_b128 v[2:5], v1 offset:25696
	s_waitcnt lgkmcnt(8)
	v_mfma_f32_32x32x16_bf16 v[80:95], v[228:231], v[168:171], v[80:95]
	s_waitcnt lgkmcnt(7)
	v_mfma_f32_32x32x16_bf16 v[96:111], v[216:219], v[172:175], v[96:111]
	s_waitcnt lgkmcnt(5)
	v_mfma_f32_32x32x16_bf16 v[80:95], v[236:239], v[172:175], v[80:95]
	v_mfma_f32_32x32x16_bf16 v[96:111], v[232:235], v[176:179], v[96:111]
	s_waitcnt lgkmcnt(4)
	v_mfma_f32_32x32x16_bf16 v[80:95], v[240:243], v[176:179], v[80:95]
	s_nop 15
	s_nop 3
	s_nop 0
	v_max3_f32 v14, v96, v97, v98
	v_max3_f32 v215, v99, v100, v101
	v_max3_f32 v15, v80, v81, v82
	v_max3_f32 v216, v83, v84, v85
	v_max3_f32 v217, v102, v103, v104
	v_max3_f32 v218, v86, v87, v88
	v_max3_f32 v220, v89, v90, v91
	v_max3_f32 v219, v105, v106, v107
	v_max3_f32 v221, v108, v109, v110
	v_max3_f32 v222, v92, v93, v94
	s_nop 0
	v_max3_f32 v14, v14, v215, v217
	v_max3_f32 v215, v216, v218, v220
	v_max3_f32 v15, v219, v221, v15
	v_max3_f32 v216, v222, v111, v95
	s_nop 0
	v_max3_f32 v14, v14, v15, v215
	v_and_b32_e32 v215, 64, v212
	v_xor_b32_e32 v15, 32, v212
	v_add_u32_e32 v215, 64, v215
	v_cmp_lt_i32_e32 vcc, v15, v215
	v_max3_f32 v14, v14, v216, v216
	v_sub_f32_e32 v216, v14, v214
	v_cmp_ge_f32_e64 s[98:99], s43, v216
	s_cmp_eq_u64 s[98:99], exec
	s_cbranch_scc1 .Lattn_nobp
	s_nop 1
	v_cndmask_b32_e32 v15, v212, v15, vcc
	v_lshlrev_b32_e32 v15, 2, v15
	ds_bpermute_b32 v15, v15, v14
	v_max_f32_e32 v14, v14, v14
	s_waitcnt lgkmcnt(0)
	v_max_f32_e32 v15, v15, v15
	v_max_f32_e32 v14, v14, v15
	v_sub_f32_e32 v15, v14, v214
	v_cmp_ge_f32_e32 vcc, s43, v15
	s_cmp_eq_u64 vcc, exec
	s_cbranch_scc1 .LBB0_963
	v_max_f32_e32 v14, v14, v14
	v_max_f32_e32 v15, v214, v214
	v_max_f32_e32 v15, v15, v14
	v_sub_f32_e32 v14, v214, v15
	v_exp_f32_e32 v14, v14
	v_mov_b32_e32 v214, v15
	s_mov_b32 s100, 1
	v_pk_mul_f32 v[78:79], v[78:79], v[14:15] op_sel_hi:[1,0]
	v_pk_mul_f32 v[76:77], v[76:77], v[14:15] op_sel_hi:[1,0]
	v_pk_mul_f32 v[74:75], v[74:75], v[14:15] op_sel_hi:[1,0]
	v_pk_mul_f32 v[72:73], v[72:73], v[14:15] op_sel_hi:[1,0]
	v_pk_mul_f32 v[70:71], v[70:71], v[14:15] op_sel_hi:[1,0]
	v_pk_mul_f32 v[68:69], v[68:69], v[14:15] op_sel_hi:[1,0]
	v_pk_mul_f32 v[66:67], v[66:67], v[14:15] op_sel_hi:[1,0]
	v_pk_mul_f32 v[64:65], v[64:65], v[14:15] op_sel_hi:[1,0]
	v_pk_mul_f32 v[62:63], v[62:63], v[14:15] op_sel_hi:[1,0]
	v_pk_mul_f32 v[60:61], v[60:61], v[14:15] op_sel_hi:[1,0]
	v_pk_mul_f32 v[58:59], v[58:59], v[14:15] op_sel_hi:[1,0]
	v_pk_mul_f32 v[56:57], v[56:57], v[14:15] op_sel_hi:[1,0]
	v_pk_mul_f32 v[54:55], v[54:55], v[14:15] op_sel_hi:[1,0]
	v_pk_mul_f32 v[52:53], v[52:53], v[14:15] op_sel_hi:[1,0]
	v_pk_mul_f32 v[50:51], v[50:51], v[14:15] op_sel_hi:[1,0]
	v_pk_mul_f32 v[48:49], v[48:49], v[14:15] op_sel_hi:[1,0]
	v_pk_mul_f32 v[46:47], v[46:47], v[14:15] op_sel_hi:[1,0]
	v_pk_mul_f32 v[44:45], v[44:45], v[14:15] op_sel_hi:[1,0]
	v_pk_mul_f32 v[42:43], v[42:43], v[14:15] op_sel_hi:[1,0]
	v_pk_mul_f32 v[40:41], v[40:41], v[14:15] op_sel_hi:[1,0]
	v_pk_mul_f32 v[38:39], v[38:39], v[14:15] op_sel_hi:[1,0]
	v_pk_mul_f32 v[36:37], v[36:37], v[14:15] op_sel_hi:[1,0]
	v_pk_mul_f32 v[34:35], v[34:35], v[14:15] op_sel_hi:[1,0]
	v_pk_mul_f32 v[32:33], v[32:33], v[14:15] op_sel_hi:[1,0]
	v_pk_mul_f32 v[30:31], v[30:31], v[14:15] op_sel_hi:[1,0]
	v_pk_mul_f32 v[28:29], v[28:29], v[14:15] op_sel_hi:[1,0]
	v_pk_mul_f32 v[26:27], v[26:27], v[14:15] op_sel_hi:[1,0]
	v_pk_mul_f32 v[24:25], v[24:25], v[14:15] op_sel_hi:[1,0]
	v_pk_mul_f32 v[22:23], v[22:23], v[14:15] op_sel_hi:[1,0]
	v_pk_mul_f32 v[20:21], v[20:21], v[14:15] op_sel_hi:[1,0]
	v_pk_mul_f32 v[18:19], v[18:19], v[14:15] op_sel_hi:[1,0]
	v_pk_mul_f32 v[16:17], v[16:17], v[14:15] op_sel_hi:[1,0]
	v_mul_f32_e32 v213, v213, v14
.LBB0_963:
	s_cmp_eq_u32 s100, 0
	s_cbranch_scc1 .Lattn_fast
	v_sub_f32_e32 v15, v80, v214
	v_sub_f32_e32 v80, v97, v214
	v_exp_f32_e32 v216, v80
	v_sub_f32_e32 v80, v81, v214
	v_exp_f32_e32 v217, v80
	v_sub_f32_e32 v80, v98, v214
	v_exp_f32_e32 v218, v80
	v_sub_f32_e32 v80, v82, v214
	v_exp_f32_e32 v219, v80
	v_sub_f32_e32 v80, v99, v214
	v_exp_f32_e32 v220, v80
	v_sub_f32_e32 v80, v83, v214
	v_exp_f32_e32 v221, v80
	v_sub_f32_e32 v80, v100, v214
	v_exp_f32_e32 v222, v80
	v_sub_f32_e32 v80, v84, v214
	v_exp_f32_e32 v223, v80
	v_sub_f32_e32 v80, v101, v214
	v_exp_f32_e32 v224, v80
	v_sub_f32_e32 v80, v85, v214
	v_exp_f32_e32 v225, v80
	v_sub_f32_e32 v80, v102, v214
	v_exp_f32_e32 v226, v80
	v_sub_f32_e32 v80, v86, v214
	v_exp_f32_e32 v227, v80
	v_sub_f32_e32 v80, v103, v214
	v_exp_f32_e32 v228, v80
	v_sub_f32_e32 v80, v87, v214
	v_exp_f32_e32 v229, v80
	v_sub_f32_e32 v80, v104, v214
	v_exp_f32_e32 v230, v80
	v_sub_f32_e32 v80, v88, v214
	v_exp_f32_e32 v231, v80
	v_sub_f32_e32 v80, v105, v214
	v_exp_f32_e32 v232, v80
	v_sub_f32_e32 v80, v89, v214
	v_exp_f32_e32 v233, v80
	v_sub_f32_e32 v80, v106, v214
	v_exp_f32_e32 v234, v80
	v_sub_f32_e32 v80, v90, v214
	v_exp_f32_e32 v235, v80
	v_sub_f32_e32 v80, v107, v214
	v_exp_f32_e32 v236, v80
	v_sub_f32_e32 v80, v91, v214
	v_exp_f32_e32 v237, v80
	v_sub_f32_e32 v80, v108, v214
	v_exp_f32_e32 v238, v80
	v_sub_f32_e32 v80, v92, v214
	v_exp_f32_e32 v239, v80
	v_sub_f32_e32 v80, v109, v214
	v_exp_f32_e32 v240, v80
	v_sub_f32_e32 v80, v93, v214
	v_exp_f32_e32 v241, v80
	v_sub_f32_e32 v80, v110, v214
	v_exp_f32_e32 v242, v80
	v_sub_f32_e32 v80, v94, v214
	v_exp_f32_e32 v243, v80
	v_sub_f32_e32 v80, v111, v214
	v_sub_f32_e32 v14, v96, v214
	v_exp_f32_e32 v244, v80
	v_sub_f32_e32 v80, v95, v214
	v_exp_f32_e32 v14, v14
	v_exp_f32_e32 v15, v15
	v_exp_f32_e32 v245, v80
